# v15 plus saddr-form DMA in J mainloop plus all s_setprio removed from the GEMM mainloops
# speedup vs baseline: 1.0098x; 1.0008x over previous
; #define PG8_STAGE(bufoff, gbase, voff) do { _Pragma("unroll") for (int _i = 0; _i < 2; ++_i) \
;         __builtin_amdgcn_global_load_lds((const unsigned*)((const char*)(gbase) + (voff)[_i]), (LAS unsigned*)(lds + (bufoff) + ldsw + _i * 8192), 16, 0, 0); } while (0)
; #define PG8_LDA(dst, b, h) do { _Pragma("unroll") for (int m = 0; m < 4; ++m) _Pragma("unroll") for (int k = 0; k < 2; ++k) dst[m][k] = *(const LAS bf16x8*)(lds + PG8_SA(b, h) + aoff + m * 2048 + k * 1024); } while (0)
; #define PG8_LDB(dst, b, h) do { _Pragma("unroll") for (int n = 0; n < 2; ++n) _Pragma("unroll") for (int k = 0; k < 2; ++k) dst[n][k] = *(const LAS bf16x8*)(lds + PG8_SB(b, h) + boff + n * 2048 + k * 1024); } while (0)
; #define PG8_MMA(ai, bj, At, Bt) do { __builtin_amdgcn_s_setprio(1); _Pragma("unroll") for (int m = 0; m < 4; ++m) _Pragma("unroll") for (int n = 0; n < 2; ++n) _Pragma("unroll") for (int k = 0; k < 2; ++k) \
;         acc[ai][bj][m][n] = __builtin_amdgcn_mfma_f32_16x16x32_bf16(Bt[n][k], At[m][k], acc[ai][bj][m][n], 0, 0, 0); __builtin_amdgcn_s_setprio(0); } while (0)
; #define PG8_WAIT_V(n) asm volatile("s_waitcnt vmcnt(" #n ")" ::: "memory")
; #define PG8_WAIT_L(n) asm volatile("s_waitcnt lgkmcnt(" #n ")" ::: "memory")
; #define PG8_BAR __builtin_amdgcn_s_barrier()
; #define PG8_SCHED __builtin_amdgcn_sched_barrier(0)
; template <class Epi>
; __device__ __forceinline__ void gemm_phase(LAS unsigned char* lds, const Sched& S, const int K, const Epi& E) {
;     ...
;             const char* a1 = cA + (size_t)(t + 1) * kstep;
;             const char* a2 = last ? nA : cA + (size_t)(t + 2) * kstep; const char* b2 = last ? nB : cB + (size_t)(t + 2) * kstep;
;             const char* a3 = a2 + kstep; const char* b3 = b2 + kstep;
;             PG8_LDB(B0, 0, 0); PG8_LDB(B1, 0, 1); PG8_SCHED; PG8_LDA(At, 0, 0); PG8_STAGE(PG8_SA(1, 1), a1 + hstepA, voffA);
;             PG8_WAIT_V(8); PG8_WAIT_L(0); PG8_BAR; PG8_MMA(0, 0, At, B0); PG8_MMA(0, 1, At, B1); PG8_BAR; PG8_SCHED;
;             PG8_LDA(At, 0, 1); PG8_STAGE(PG8_SB(0, 0), b2, voffB); PG8_STAGE(PG8_SB(0, 1), b2 + hstepB, voffB); PG8_STAGE(PG8_SA(0, 0), a2, voffA);
;             PG8_WAIT_V(8); PG8_WAIT_L(0); PG8_BAR; PG8_MMA(1, 0, At, B0); PG8_MMA(1, 1, At, B1); PG8_BAR; PG8_SCHED;
.LBB0_1400:
	s_add_u32 s50, s36, 0xfff80080
	s_addc_u32 s51, s37, -1
	s_add_i32 s73, 0, 0x10000
	s_cmp_eq_u32 s72, 28
	s_cselect_b32 s53, s29, s51
	s_cselect_b32 s52, s28, s50
	s_cselect_b32 s51, s35, s71
	s_cselect_b32 s50, s34, s45
	s_add_i32 s78, 0, 0x14000
	v_add_u32_e32 v154, s73, v139
	v_add_u32_e32 v170, s78, v139
	ds_read_b128 v[142:145], v154
	ds_read_b128 v[146:149], v154 offset:1024
	ds_read_b128 v[150:153], v154 offset:2048
	ds_read_b128 v[154:157], v154 offset:3072
	ds_read_b128 v[158:161], v170
	ds_read_b128 v[162:165], v170 offset:1024
	ds_read_b128 v[166:169], v170 offset:2048
	ds_read_b128 v[198:201], v170 offset:3072
	s_add_i32 m0, s59, 0xc000
	ds_read_b128 v[202:205], v141
	ds_read_b128 v[206:209], v141 offset:1024
	ds_read_b128 v[210:213], v141 offset:2048
	ds_read_b128 v[214:217], v141 offset:3072
	ds_read_b128 v[218:221], v141 offset:4096
	ds_read_b128 v[228:231], v141 offset:5120
	ds_read_b128 v[232:235], v141 offset:6144
	ds_read_b128 v[236:239], v141 offset:7168
	global_load_lds_dwordx4 v134, s[36:37]
	s_add_i32 m0, s59, 0xe000
	s_nop 0
	global_load_lds_dwordx4 v136, s[36:37]
	s_waitcnt vmcnt(8)
	s_waitcnt lgkmcnt(0)
	s_barrier
	s_waitcnt lgkmcnt(0)
	v_mfma_f32_16x16x32_bf16 v[124:127], v[142:145], v[202:205], v[124:127]
	v_mfma_f32_16x16x32_bf16 v[116:119], v[150:153], v[202:205], v[116:119]
	v_mfma_f32_16x16x32_bf16 v[108:111], v[142:145], v[210:213], v[108:111]
	v_mfma_f32_16x16x32_bf16 v[100:103], v[150:153], v[210:213], v[100:103]
	v_mfma_f32_16x16x32_bf16 v[92:95], v[142:145], v[218:221], v[92:95]
	v_mfma_f32_16x16x32_bf16 v[84:87], v[150:153], v[218:221], v[84:87]
	v_mfma_f32_16x16x32_bf16 v[76:79], v[142:145], v[232:235], v[76:79]
	v_mfma_f32_16x16x32_bf16 v[68:71], v[150:153], v[232:235], v[68:71]
	v_mfma_f32_16x16x32_bf16 v[124:127], v[146:149], v[206:209], v[124:127]
	v_mfma_f32_16x16x32_bf16 v[116:119], v[154:157], v[206:209], v[116:119]
	v_mfma_f32_16x16x32_bf16 v[108:111], v[146:149], v[214:217], v[108:111]
	v_mfma_f32_16x16x32_bf16 v[100:103], v[154:157], v[214:217], v[100:103]
	v_mfma_f32_16x16x32_bf16 v[92:95], v[146:149], v[228:231], v[92:95]
	v_mfma_f32_16x16x32_bf16 v[84:87], v[154:157], v[228:231], v[84:87]
	v_mfma_f32_16x16x32_bf16 v[76:79], v[146:149], v[236:239], v[76:79]
	v_mfma_f32_16x16x32_bf16 v[68:71], v[154:157], v[236:239], v[68:71]
	v_mfma_f32_16x16x32_bf16 v[120:123], v[158:161], v[202:205], v[120:123]
	v_mfma_f32_16x16x32_bf16 v[112:115], v[166:169], v[202:205], v[112:115]
	v_mfma_f32_16x16x32_bf16 v[104:107], v[158:161], v[210:213], v[104:107]
	v_mfma_f32_16x16x32_bf16 v[96:99], v[166:169], v[210:213], v[96:99]
	v_mfma_f32_16x16x32_bf16 v[88:91], v[158:161], v[218:221], v[88:91]
	v_mfma_f32_16x16x32_bf16 v[80:83], v[166:169], v[218:221], v[80:83]
	v_mfma_f32_16x16x32_bf16 v[72:75], v[158:161], v[232:235], v[72:75]
	v_mfma_f32_16x16x32_bf16 v[64:67], v[166:169], v[232:235], v[64:67]
	v_mfma_f32_16x16x32_bf16 v[120:123], v[162:165], v[206:209], v[120:123]
	v_mfma_f32_16x16x32_bf16 v[112:115], v[198:201], v[206:209], v[112:115]
	v_mfma_f32_16x16x32_bf16 v[104:107], v[162:165], v[214:217], v[104:107]
	v_mfma_f32_16x16x32_bf16 v[96:99], v[198:201], v[214:217], v[96:99]
	v_mfma_f32_16x16x32_bf16 v[88:91], v[162:165], v[228:231], v[88:91]
	v_mfma_f32_16x16x32_bf16 v[80:83], v[198:201], v[228:231], v[80:83]
	v_mfma_f32_16x16x32_bf16 v[72:75], v[162:165], v[236:239], v[72:75]
	v_mfma_f32_16x16x32_bf16 v[64:67], v[198:201], v[236:239], v[64:67]
	s_barrier
	s_add_i32 s73, s73, s58
	s_mov_b32 m0, s73
	ds_read_b128 v[202:205], v141 offset:16384
	ds_read_b128 v[206:209], v141 offset:17408
	ds_read_b128 v[210:213], v141 offset:18432
	ds_read_b128 v[214:217], v141 offset:19456
	ds_read_b128 v[218:221], v141 offset:20480
	ds_read_b128 v[228:231], v141 offset:21504
	ds_read_b128 v[232:235], v141 offset:22528
	ds_read_b128 v[236:239], v141 offset:23552
	global_load_lds_dwordx4 v172, s[50:51]
	s_add_i32 m0, s73, 0x2000
	s_add_u32 s76, s50, 0x80000
	s_addc_u32 s77, s51, 0
	s_add_i32 s73, s78, s58
	global_load_lds_dwordx4 v128, s[50:51]
	s_mov_b32 m0, s73
	s_nop 0
	global_load_lds_dwordx4 v172, s[76:77]
	s_add_i32 m0, s73, 0x2000
	s_nop 0
	global_load_lds_dwordx4 v128, s[76:77]
	s_mov_b32 m0, s59
	s_nop 0
	global_load_lds_dwordx4 v132, s[52:53]
	s_mov_b32 m0, s60
	s_nop 0
	global_load_lds_dwordx4 v130, s[52:53]
	s_waitcnt vmcnt(8)
	s_waitcnt lgkmcnt(0)
	s_barrier
	s_waitcnt lgkmcnt(0)
	v_mfma_f32_16x16x32_bf16 v[60:63], v[142:145], v[202:205], v[60:63]
	v_mfma_f32_16x16x32_bf16 v[52:55], v[150:153], v[202:205], v[52:55]
	v_mfma_f32_16x16x32_bf16 v[44:47], v[142:145], v[210:213], v[44:47]
	v_mfma_f32_16x16x32_bf16 v[36:39], v[150:153], v[210:213], v[36:39]
	v_mfma_f32_16x16x32_bf16 v[28:31], v[142:145], v[218:221], v[28:31]
	v_mfma_f32_16x16x32_bf16 v[20:23], v[150:153], v[218:221], v[20:23]
	v_mfma_f32_16x16x32_bf16 v[12:15], v[142:145], v[232:235], v[12:15]
	v_mfma_f32_16x16x32_bf16 v[4:7], v[150:153], v[232:235], v[4:7]
	v_mfma_f32_16x16x32_bf16 v[60:63], v[146:149], v[206:209], v[60:63]
	v_mfma_f32_16x16x32_bf16 v[52:55], v[154:157], v[206:209], v[52:55]
	v_mfma_f32_16x16x32_bf16 v[44:47], v[146:149], v[214:217], v[44:47]
	v_mfma_f32_16x16x32_bf16 v[36:39], v[154:157], v[214:217], v[36:39]
	v_mfma_f32_16x16x32_bf16 v[28:31], v[146:149], v[228:231], v[28:31]
	v_mfma_f32_16x16x32_bf16 v[20:23], v[154:157], v[228:231], v[20:23]
	v_mfma_f32_16x16x32_bf16 v[12:15], v[146:149], v[236:239], v[12:15]
	v_mfma_f32_16x16x32_bf16 v[4:7], v[154:157], v[236:239], v[4:7]
	v_mfma_f32_16x16x32_bf16 v[56:59], v[158:161], v[202:205], v[56:59]
	v_mfma_f32_16x16x32_bf16 v[48:51], v[166:169], v[202:205], v[48:51]
	v_mfma_f32_16x16x32_bf16 v[40:43], v[158:161], v[210:213], v[40:43]
	v_mfma_f32_16x16x32_bf16 v[32:35], v[166:169], v[210:213], v[32:35]
	v_mfma_f32_16x16x32_bf16 v[24:27], v[158:161], v[218:221], v[24:27]
	v_mfma_f32_16x16x32_bf16 v[16:19], v[166:169], v[218:221], v[16:19]
	v_mfma_f32_16x16x32_bf16 v[8:11], v[158:161], v[232:235], v[8:11]
	v_mfma_f32_16x16x32_bf16 v[0:3], v[166:169], v[232:235], v[0:3]
	v_mfma_f32_16x16x32_bf16 v[56:59], v[162:165], v[206:209], v[56:59]
	v_mfma_f32_16x16x32_bf16 v[48:51], v[198:201], v[206:209], v[48:51]
	v_mfma_f32_16x16x32_bf16 v[40:43], v[162:165], v[214:217], v[40:43]
	v_mfma_f32_16x16x32_bf16 v[32:35], v[198:201], v[214:217], v[32:35]
	v_mfma_f32_16x16x32_bf16 v[24:27], v[162:165], v[228:231], v[24:27]
	v_mfma_f32_16x16x32_bf16 v[16:19], v[198:201], v[228:231], v[16:19]
	v_mfma_f32_16x16x32_bf16 v[8:11], v[162:165], v[236:239], v[8:11]
	v_mfma_f32_16x16x32_bf16 v[0:3], v[198:201], v[236:239], v[0:3]
	s_barrier
; #define PG8_STAGE(bufoff, gbase, voff) do { _Pragma("unroll") for (int _i = 0; _i < 2; ++_i) \
;         __builtin_amdgcn_global_load_lds((const unsigned*)((const char*)(gbase) + (voff)[_i]), (LAS unsigned*)(lds + (bufoff) + ldsw + _i * 8192), 16, 0, 0); } while (0)
; #define PG8_LDA(dst, b, h) do { _Pragma("unroll") for (int m = 0; m < 4; ++m) _Pragma("unroll") for (int k = 0; k < 2; ++k) dst[m][k] = *(const LAS bf16x8*)(lds + PG8_SA(b, h) + aoff + m * 2048 + k * 1024); } while (0)
; #define PG8_LDB(dst, b, h) do { _Pragma("unroll") for (int n = 0; n < 2; ++n) _Pragma("unroll") for (int k = 0; k < 2; ++k) dst[n][k] = *(const LAS bf16x8*)(lds + PG8_SB(b, h) + boff + n * 2048 + k * 1024); } while (0)
; #define PG8_MMA(ai, bj, At, Bt) do { __builtin_amdgcn_s_setprio(1); _Pragma("unroll") for (int m = 0; m < 4; ++m) _Pragma("unroll") for (int n = 0; n < 2; ++n) _Pragma("unroll") for (int k = 0; k < 2; ++k) \
;         acc[ai][bj][m][n] = __builtin_amdgcn_mfma_f32_16x16x32_bf16(Bt[n][k], At[m][k], acc[ai][bj][m][n], 0, 0, 0); __builtin_amdgcn_s_setprio(0); } while (0)
; #define PG8_WAIT_V(n) asm volatile("s_waitcnt vmcnt(" #n ")" ::: "memory")
; #define PG8_WAIT_L(n) asm volatile("s_waitcnt lgkmcnt(" #n ")" ::: "memory")
; #define PG8_BAR __builtin_amdgcn_s_barrier()
; #define PG8_SCHED __builtin_amdgcn_sched_barrier(0)
; template <class Epi>
; __device__ __forceinline__ void gemm_phase(LAS unsigned char* lds, const Sched& S, const int K, const Epi& E) {
;     ...
;             PG8_LDB(B0, 1, 0); PG8_LDB(B1, 1, 1); PG8_SCHED; PG8_LDA(At, 1, 0); PG8_STAGE(PG8_SA(0, 1), a2 + hstepA, voffA);
;             PG8_WAIT_V(8); PG8_WAIT_L(0); PG8_BAR; PG8_MMA(0, 0, At, B0); PG8_MMA(0, 1, At, B1); PG8_BAR; PG8_SCHED;
;             PG8_LDA(At, 1, 1); PG8_STAGE(PG8_SB(1, 0), b3, voffB); PG8_STAGE(PG8_SB(1, 1), b3 + hstepB, voffB); PG8_STAGE(PG8_SA(1, 0), a3, voffA);
;             PG8_WAIT_V(8); PG8_WAIT_L(0); PG8_BAR; PG8_MMA(1, 0, At, B0); PG8_MMA(1, 1, At, B1); PG8_BAR; PG8_SCHED;
;         }
	s_add_i32 s73, 0, 0x18000
	s_add_i32 s76, 0, 0x1c000
	v_add_u32_e32 v154, s73, v139
	v_add_u32_e32 v198, s76, v139
	ds_read_b128 v[142:145], v154
	ds_read_b128 v[146:149], v154 offset:1024
	ds_read_b128 v[150:153], v154 offset:2048
	ds_read_b128 v[154:157], v154 offset:3072
	ds_read_b128 v[158:161], v198
	ds_read_b128 v[162:165], v198 offset:1024
	ds_read_b128 v[166:169], v198 offset:2048
	ds_read_b128 v[198:201], v198 offset:3072
	s_add_u32 s52, s52, 0x80000
	s_addc_u32 s53, s53, 0
	s_mov_b32 m0, s63
	ds_read_b128 v[202:205], v141 offset:32768
	ds_read_b128 v[206:209], v141 offset:33792
	ds_read_b128 v[210:213], v141 offset:34816
	ds_read_b128 v[214:217], v141 offset:35840
	ds_read_b128 v[218:221], v141 offset:36864
	ds_read_b128 v[228:231], v141 offset:37888
	ds_read_b128 v[232:235], v141 offset:38912
	ds_read_b128 v[236:239], v141 offset:39936
	global_load_lds_dwordx4 v132, s[52:53]
	s_mov_b32 m0, s65
	s_nop 0
	global_load_lds_dwordx4 v130, s[52:53]
	s_waitcnt vmcnt(8)
	s_waitcnt lgkmcnt(0)
	s_barrier
	s_waitcnt lgkmcnt(0)
	v_mfma_f32_16x16x32_bf16 v[124:127], v[142:145], v[202:205], v[124:127]
	v_mfma_f32_16x16x32_bf16 v[116:119], v[150:153], v[202:205], v[116:119]
	v_mfma_f32_16x16x32_bf16 v[108:111], v[142:145], v[210:213], v[108:111]
	v_mfma_f32_16x16x32_bf16 v[100:103], v[150:153], v[210:213], v[100:103]
	v_mfma_f32_16x16x32_bf16 v[92:95], v[142:145], v[218:221], v[92:95]
	v_mfma_f32_16x16x32_bf16 v[84:87], v[150:153], v[218:221], v[84:87]
	v_mfma_f32_16x16x32_bf16 v[76:79], v[142:145], v[232:235], v[76:79]
	v_mfma_f32_16x16x32_bf16 v[68:71], v[150:153], v[232:235], v[68:71]
	v_mfma_f32_16x16x32_bf16 v[124:127], v[146:149], v[206:209], v[124:127]
	v_mfma_f32_16x16x32_bf16 v[116:119], v[154:157], v[206:209], v[116:119]
	v_mfma_f32_16x16x32_bf16 v[108:111], v[146:149], v[214:217], v[108:111]
	v_mfma_f32_16x16x32_bf16 v[100:103], v[154:157], v[214:217], v[100:103]
	v_mfma_f32_16x16x32_bf16 v[92:95], v[146:149], v[228:231], v[92:95]
	v_mfma_f32_16x16x32_bf16 v[84:87], v[154:157], v[228:231], v[84:87]
	v_mfma_f32_16x16x32_bf16 v[76:79], v[146:149], v[236:239], v[76:79]
	v_mfma_f32_16x16x32_bf16 v[68:71], v[154:157], v[236:239], v[68:71]
	v_mfma_f32_16x16x32_bf16 v[120:123], v[158:161], v[202:205], v[120:123]
	v_mfma_f32_16x16x32_bf16 v[112:115], v[166:169], v[202:205], v[112:115]
	v_mfma_f32_16x16x32_bf16 v[104:107], v[158:161], v[210:213], v[104:107]
	v_mfma_f32_16x16x32_bf16 v[96:99], v[166:169], v[210:213], v[96:99]
	v_mfma_f32_16x16x32_bf16 v[88:91], v[158:161], v[218:221], v[88:91]
	v_mfma_f32_16x16x32_bf16 v[80:83], v[166:169], v[218:221], v[80:83]
	v_mfma_f32_16x16x32_bf16 v[72:75], v[158:161], v[232:235], v[72:75]
	v_mfma_f32_16x16x32_bf16 v[64:67], v[166:169], v[232:235], v[64:67]
	v_mfma_f32_16x16x32_bf16 v[120:123], v[162:165], v[206:209], v[120:123]
	v_mfma_f32_16x16x32_bf16 v[112:115], v[198:201], v[206:209], v[112:115]
	v_mfma_f32_16x16x32_bf16 v[104:107], v[162:165], v[214:217], v[104:107]
	v_mfma_f32_16x16x32_bf16 v[96:99], v[198:201], v[214:217], v[96:99]
	v_mfma_f32_16x16x32_bf16 v[88:91], v[162:165], v[228:231], v[88:91]
	v_mfma_f32_16x16x32_bf16 v[80:83], v[198:201], v[228:231], v[80:83]
	v_mfma_f32_16x16x32_bf16 v[72:75], v[162:165], v[236:239], v[72:75]
	v_mfma_f32_16x16x32_bf16 v[64:67], v[198:201], v[236:239], v[64:67]
	s_barrier
	s_add_u32 vcc_lo, s52, 0xfff80080
	s_addc_u32 vcc_hi, s53, -1
	s_add_i32 s52, s73, s58
	s_add_i32 m0, s52, 0xffffff80
	ds_read_b128 v[202:205], v141 offset:49152
	ds_read_b128 v[206:209], v141 offset:50176
	ds_read_b128 v[210:213], v141 offset:51200
	ds_read_b128 v[214:217], v141 offset:52224
	ds_read_b128 v[218:221], v141 offset:53248
	ds_read_b128 v[228:231], v141 offset:54272
	ds_read_b128 v[232:235], v141 offset:55296
	ds_read_b128 v[236:239], v141 offset:56320
	global_load_lds_dwordx4 v172, s[50:51] offset:128
	s_add_i32 m0, s52, 0x1f80
	s_nop 0
	global_load_lds_dwordx4 v128, s[50:51] offset:128
	s_add_u32 s50, s50, 0x80080
	s_addc_u32 s51, s51, 0
	s_add_i32 s52, s76, s58
	s_mov_b32 m0, s52
	s_nop 0
	global_load_lds_dwordx4 v172, s[50:51]
	s_add_i32 m0, s52, 0x2000
	s_nop 0
	global_load_lds_dwordx4 v128, s[50:51]
	s_mov_b32 m0, s66
	s_nop 0
	global_load_lds_dwordx4 v132, vcc
	s_mov_b32 m0, s67
	s_nop 0
	global_load_lds_dwordx4 v130, vcc
	s_waitcnt vmcnt(8)
	s_waitcnt lgkmcnt(0)
	s_barrier
	s_waitcnt lgkmcnt(0)
	v_mfma_f32_16x16x32_bf16 v[60:63], v[142:145], v[202:205], v[60:63]
	v_mfma_f32_16x16x32_bf16 v[52:55], v[150:153], v[202:205], v[52:55]
	v_mfma_f32_16x16x32_bf16 v[44:47], v[142:145], v[210:213], v[44:47]
	v_mfma_f32_16x16x32_bf16 v[36:39], v[150:153], v[210:213], v[36:39]
	v_mfma_f32_16x16x32_bf16 v[28:31], v[142:145], v[218:221], v[28:31]
	v_mfma_f32_16x16x32_bf16 v[20:23], v[150:153], v[218:221], v[20:23]
	v_mfma_f32_16x16x32_bf16 v[12:15], v[142:145], v[232:235], v[12:15]
	v_mfma_f32_16x16x32_bf16 v[4:7], v[150:153], v[232:235], v[4:7]
	v_mfma_f32_16x16x32_bf16 v[60:63], v[146:149], v[206:209], v[60:63]
	v_mfma_f32_16x16x32_bf16 v[52:55], v[154:157], v[206:209], v[52:55]
	v_mfma_f32_16x16x32_bf16 v[44:47], v[146:149], v[214:217], v[44:47]
	v_mfma_f32_16x16x32_bf16 v[36:39], v[154:157], v[214:217], v[36:39]
	v_mfma_f32_16x16x32_bf16 v[28:31], v[146:149], v[228:231], v[28:31]
	v_mfma_f32_16x16x32_bf16 v[20:23], v[154:157], v[228:231], v[20:23]
	v_mfma_f32_16x16x32_bf16 v[12:15], v[146:149], v[236:239], v[12:15]
	v_mfma_f32_16x16x32_bf16 v[4:7], v[154:157], v[236:239], v[4:7]
	v_mfma_f32_16x16x32_bf16 v[56:59], v[158:161], v[202:205], v[56:59]
	v_mfma_f32_16x16x32_bf16 v[48:51], v[166:169], v[202:205], v[48:51]
	v_mfma_f32_16x16x32_bf16 v[40:43], v[158:161], v[210:213], v[40:43]
	v_mfma_f32_16x16x32_bf16 v[32:35], v[166:169], v[210:213], v[32:35]
	v_mfma_f32_16x16x32_bf16 v[24:27], v[158:161], v[218:221], v[24:27]
	v_mfma_f32_16x16x32_bf16 v[16:19], v[166:169], v[218:221], v[16:19]
	v_mfma_f32_16x16x32_bf16 v[8:11], v[158:161], v[232:235], v[8:11]
	v_mfma_f32_16x16x32_bf16 v[0:3], v[166:169], v[232:235], v[0:3]
	v_mfma_f32_16x16x32_bf16 v[56:59], v[162:165], v[206:209], v[56:59]
	v_mfma_f32_16x16x32_bf16 v[48:51], v[198:201], v[206:209], v[48:51]
	v_mfma_f32_16x16x32_bf16 v[40:43], v[162:165], v[214:217], v[40:43]
	v_mfma_f32_16x16x32_bf16 v[32:35], v[198:201], v[214:217], v[32:35]
	v_mfma_f32_16x16x32_bf16 v[24:27], v[162:165], v[228:231], v[24:27]
	v_mfma_f32_16x16x32_bf16 v[16:19], v[198:201], v[228:231], v[16:19]
	v_mfma_f32_16x16x32_bf16 v[8:11], v[162:165], v[236:239], v[8:11]
	v_mfma_f32_16x16x32_bf16 v[0:3], v[198:201], v[236:239], v[0:3]
	s_barrier
	s_add_i32 s72, s72, 2
	s_add_u32 s45, s45, 0x100
	s_addc_u32 s71, s71, 0
	s_add_u32 s36, s36, 0x100
	s_addc_u32 s37, s37, 0
	s_cmp_gt_u32 s72, 29
	s_cbranch_scc0 .LBB0_1400
	s_and_b64 vcc, exec, s[42:43]
	s_cbranch_vccz .LBB0_1403
	s_barrier
